# seam barriers: non-leader L1 invalidate (buffer_inv sc1) issued before the generation spin instead of after it
# speedup vs baseline: 1.0073x; 1.0073x over previous
.LBB0_447:
	s_or_b64 exec, exec, s[8:9]
	v_cvt_f32_u32_e32 v6, v4
	s_waitcnt vmcnt(0)
	v_readfirstlane_b32 s3, v5
	v_sub_u32_e32 v5, 0, v4
	v_rcp_iflag_f32_e32 v6, v6
	v_add_u32_e32 v7, s3, v3
	v_mul_f32_e32 v6, 0x4f7ffffe, v6
	v_cvt_u32_f32_e32 v6, v6
	v_mul_lo_u32 v3, v5, v6
	v_mul_hi_u32 v3, v6, v3
	v_add_u32_e32 v3, v6, v3
	v_mul_hi_u32 v3, v7, v3
	v_mul_lo_u32 v5, v3, v4
	v_sub_u32_e32 v5, v7, v5
	v_add_u32_e32 v6, 1, v3
	v_cmp_ge_u32_e32 vcc, v5, v4
	s_nop 1
	v_cndmask_b32_e32 v3, v3, v6, vcc
	v_sub_u32_e32 v6, v5, v4
	v_cndmask_b32_e32 v5, v5, v6, vcc
	v_add_u32_e32 v6, 1, v3
	v_cmp_ge_u32_e32 vcc, v5, v4
	v_add_u32_e32 v5, 1, v7
	s_nop 0
	v_cndmask_b32_e32 v3, v3, v6, vcc
	v_mul_lo_u32 v6, v4, v3
	v_add_u32_e32 v4, v6, v4
	v_cmp_ne_u32_e32 vcc, v5, v4
	s_and_saveexec_b64 s[6:7], vcc
	s_xor_b64 s[6:7], exec, s[6:7]
	s_cbranch_execz .LBB0_461
	s_waitcnt lgkmcnt(0)
	v_mov_b32_e32 v2, 0x2000
	buffer_inv sc1
	global_load_dword v2, v2, s[4:5] offset:1024 sc1
	s_add_u32 s12, s4, 0x2400
	s_addc_u32 s13, s5, 0
	s_waitcnt vmcnt(0)
	v_cmp_eq_u32_e32 vcc, v2, v3
	s_and_saveexec_b64 s[8:9], vcc
	s_cbranch_execz .LBB0_460
	s_add_u32 s10, s34, 0x4200
	s_addc_u32 s11, s35, 0
	s_mov_b32 s3, 1
	s_mov_b64 s[14:15], 0
	v_mov_b32_e32 v2, 0
	s_branch .LBB0_451

.LBB0_460:
	s_or_b64 exec, exec, s[8:9]
	s_waitcnt vmcnt(0)
	s_waitcnt vmcnt(0)

.LBB0_525:
	s_or_b64 exec, exec, s[8:9]
	v_cvt_f32_u32_e32 v6, v4
	s_waitcnt vmcnt(0)
	v_readfirstlane_b32 s0, v5
	v_sub_u32_e32 v5, 0, v4
	v_rcp_iflag_f32_e32 v6, v6
	v_add_u32_e32 v7, s0, v3
	v_mul_f32_e32 v6, 0x4f7ffffe, v6
	v_cvt_u32_f32_e32 v6, v6
	v_mul_lo_u32 v3, v5, v6
	v_mul_hi_u32 v3, v6, v3
	v_add_u32_e32 v3, v6, v3
	v_mul_hi_u32 v3, v7, v3
	v_mul_lo_u32 v5, v3, v4
	v_sub_u32_e32 v5, v7, v5
	v_add_u32_e32 v6, 1, v3
	v_cmp_ge_u32_e32 vcc, v5, v4
	s_nop 1
	v_cndmask_b32_e32 v3, v3, v6, vcc
	v_sub_u32_e32 v6, v5, v4
	v_cndmask_b32_e32 v5, v5, v6, vcc
	v_add_u32_e32 v6, 1, v3
	v_cmp_ge_u32_e32 vcc, v5, v4
	v_add_u32_e32 v5, 1, v7
	s_nop 0
	v_cndmask_b32_e32 v3, v3, v6, vcc
	v_mul_lo_u32 v6, v4, v3
	v_add_u32_e32 v4, v6, v4
	v_cmp_ne_u32_e32 vcc, v5, v4
	s_and_saveexec_b64 s[0:1], vcc
	s_xor_b64 s[0:1], exec, s[0:1]
	s_cbranch_execz .LBB0_539
	s_waitcnt lgkmcnt(0)
	v_mov_b32_e32 v2, 0x2000
	global_load_dword v2, v2, s[6:7] offset:1024 sc1
	buffer_inv sc1
	s_add_u32 s12, s6, 0x2400
	s_addc_u32 s13, s7, 0
	s_waitcnt vmcnt(0)
	v_cmp_eq_u32_e32 vcc, v2, v3
	s_and_saveexec_b64 s[8:9], vcc
	s_cbranch_execz .LBB0_538
	s_add_u32 s10, s34, 0x4200
	s_addc_u32 s11, s35, 0
	s_mov_b32 s3, 1
	s_mov_b64 s[14:15], 0
	v_mov_b32_e32 v2, 0
	s_branch .LBB0_529

.LBB0_631:
	s_or_b64 exec, exec, s[10:11]
	v_cvt_f32_u32_e32 v6, v4
	s_waitcnt vmcnt(0)
	v_readfirstlane_b32 s0, v5
	v_sub_u32_e32 v5, 0, v4
	v_rcp_iflag_f32_e32 v6, v6
	v_add_u32_e32 v7, s0, v3
	v_mul_f32_e32 v6, 0x4f7ffffe, v6
	v_cvt_u32_f32_e32 v6, v6
	v_mul_lo_u32 v3, v5, v6
	v_mul_hi_u32 v3, v6, v3
	v_add_u32_e32 v3, v6, v3
	v_mul_hi_u32 v3, v7, v3
	v_mul_lo_u32 v5, v3, v4
	v_sub_u32_e32 v5, v7, v5
	v_add_u32_e32 v6, 1, v3
	v_cmp_ge_u32_e32 vcc, v5, v4
	s_nop 1
	v_cndmask_b32_e32 v3, v3, v6, vcc
	v_sub_u32_e32 v6, v5, v4
	v_cndmask_b32_e32 v5, v5, v6, vcc
	v_add_u32_e32 v6, 1, v3
	v_cmp_ge_u32_e32 vcc, v5, v4
	v_add_u32_e32 v5, 1, v7
	s_nop 0
	v_cndmask_b32_e32 v3, v3, v6, vcc
	v_mul_lo_u32 v6, v4, v3
	v_add_u32_e32 v4, v6, v4
	v_cmp_ne_u32_e32 vcc, v5, v4
	s_and_saveexec_b64 s[0:1], vcc
	s_xor_b64 s[0:1], exec, s[0:1]
	s_cbranch_execz .LBB0_645
	s_waitcnt lgkmcnt(0)
	v_mov_b32_e32 v2, 0x2000
	global_load_dword v2, v2, s[8:9] offset:1024 sc1
	s_add_u32 s14, s8, 0x2400
	buffer_inv sc1
	s_addc_u32 s15, s9, 0
	s_waitcnt vmcnt(0)
	v_cmp_eq_u32_e32 vcc, v2, v3
	s_and_saveexec_b64 s[10:11], vcc
	s_cbranch_execz .LBB0_644
	s_add_u32 s12, s34, 0x4200
	s_addc_u32 s13, s35, 0
	s_mov_b32 s3, 1
	s_mov_b64 s[40:41], 0
	v_mov_b32_e32 v2, 0
	s_branch .LBB0_635

.LBB0_644:
	s_or_b64 exec, exec, s[10:11]
	s_waitcnt vmcnt(0)
	s_waitcnt vmcnt(0)

.LBB0_1258:
	s_or_b64 exec, exec, s[8:9]
	v_cvt_f32_u32_e32 v5, v3
	s_waitcnt vmcnt(0)
	v_readfirstlane_b32 s0, v4
	v_sub_u32_e32 v4, 0, v3
	v_rcp_iflag_f32_e32 v5, v5
	v_add_u32_e32 v6, s0, v2
	v_mul_f32_e32 v5, 0x4f7ffffe, v5
	v_cvt_u32_f32_e32 v5, v5
	v_mul_lo_u32 v2, v4, v5
	v_mul_hi_u32 v2, v5, v2
	v_add_u32_e32 v2, v5, v2
	v_mul_hi_u32 v2, v6, v2
	v_mul_lo_u32 v4, v2, v3
	v_sub_u32_e32 v4, v6, v4
	v_add_u32_e32 v5, 1, v2
	v_cmp_ge_u32_e32 vcc, v4, v3
	s_nop 1
	v_cndmask_b32_e32 v2, v2, v5, vcc
	v_sub_u32_e32 v5, v4, v3
	v_cndmask_b32_e32 v4, v4, v5, vcc
	v_add_u32_e32 v5, 1, v2
	v_cmp_ge_u32_e32 vcc, v4, v3
	v_add_u32_e32 v4, 1, v6
	s_nop 0
	v_cndmask_b32_e32 v2, v2, v5, vcc
	v_mul_lo_u32 v5, v3, v2
	v_add_u32_e32 v3, v5, v3
	v_cmp_ne_u32_e32 vcc, v4, v3
	s_and_saveexec_b64 s[0:1], vcc
	s_xor_b64 s[0:1], exec, s[0:1]
	s_cbranch_execz .LBB0_1272
	s_waitcnt lgkmcnt(0)
	v_mov_b32_e32 v1, 0x2000
	global_load_dword v1, v1, s[6:7] offset:1024 sc1
	s_add_u32 s12, s6, 0x2400
	s_addc_u32 s13, s7, 0
	buffer_inv sc1
	s_waitcnt vmcnt(0)
	v_cmp_eq_u32_e32 vcc, v1, v2
	s_and_saveexec_b64 s[8:9], vcc
	s_cbranch_execz .LBB0_1271
	s_add_u32 s10, s34, 0x4200
	s_addc_u32 s11, s35, 0
	s_mov_b32 s3, 1
	s_mov_b64 s[14:15], 0
	v_mov_b32_e32 v1, 0
	s_branch .LBB0_1262

.LBB0_1428:
	s_or_b64 exec, exec, s[8:9]
	v_cvt_f32_u32_e32 v5, v3
	s_waitcnt vmcnt(0)
	v_readfirstlane_b32 s0, v4
	v_sub_u32_e32 v4, 0, v3
	v_rcp_iflag_f32_e32 v5, v5
	v_add_u32_e32 v6, s0, v2
	v_mul_f32_e32 v5, 0x4f7ffffe, v5
	v_cvt_u32_f32_e32 v5, v5
	v_mul_lo_u32 v2, v4, v5
	v_mul_hi_u32 v2, v5, v2
	v_add_u32_e32 v2, v5, v2
	v_mul_hi_u32 v2, v6, v2
	v_mul_lo_u32 v4, v2, v3
	v_sub_u32_e32 v4, v6, v4
	v_add_u32_e32 v5, 1, v2
	v_cmp_ge_u32_e32 vcc, v4, v3
	s_nop 1
	v_cndmask_b32_e32 v2, v2, v5, vcc
	v_sub_u32_e32 v5, v4, v3
	v_cndmask_b32_e32 v4, v4, v5, vcc
	v_add_u32_e32 v5, 1, v2
	v_cmp_ge_u32_e32 vcc, v4, v3
	v_add_u32_e32 v4, 1, v6
	s_nop 0
	v_cndmask_b32_e32 v2, v2, v5, vcc
	v_mul_lo_u32 v5, v3, v2
	v_add_u32_e32 v3, v5, v3
	v_cmp_ne_u32_e32 vcc, v4, v3
	s_and_saveexec_b64 s[0:1], vcc
	s_xor_b64 s[0:1], exec, s[0:1]
	s_cbranch_execz .LBB0_1442
	s_waitcnt lgkmcnt(0)
	v_mov_b32_e32 v1, 0x2000
	global_load_dword v1, v1, s[6:7] offset:1024 sc1
	s_add_u32 s14, s6, 0x2400
	s_addc_u32 s15, s7, 0
	s_waitcnt vmcnt(0)
	buffer_inv sc1
	v_cmp_eq_u32_e32 vcc, v1, v2
	s_and_saveexec_b64 s[8:9], vcc
	s_cbranch_execz .LBB0_1441
	v_readlane_b32 s12, v244, 58
	v_readlane_b32 s13, v244, 59
	s_add_u32 s12, s12, 0x4200
	s_addc_u32 s13, s13, 0
	s_mov_b32 s38, 1
	s_mov_b64 s[18:19], 0
	v_mov_b32_e32 v1, 0
	s_branch .LBB0_1432

.LBB0_1467:
	s_cmp_lt_i32 s94, 6
	s_cselect_b64 s[0:1], -1, 0
	s_cmp_gt_i32 s95, 5
	s_cselect_b64 s[4:5], -1, 0
	s_and_b64 s[0:1], s[0:1], s[4:5]
	s_andn2_b64 vcc, exec, s[0:1]
	s_cbranch_vccnz .LBB0_1608
	s_abs_i32 s0, s33
	v_cvt_f32_u32_e32 v1, s0
	s_sub_i32 s5, 0, s0
	s_add_i32 s1, s33, 0x3ff
	s_xor_b32 s4, s1, s33
	v_rcp_iflag_f32_e32 v1, v1
	s_abs_i32 s1, s1
	s_ashr_i32 s4, s4, 31
	v_mul_f32_e32 v1, 0x4f7ffffe, v1
	v_cvt_u32_f32_e32 v1, v1
	s_nop 0
	v_readfirstlane_b32 s6, v1
	s_mul_i32 s5, s5, s6
	s_mul_hi_u32 s5, s6, s5
	s_add_i32 s6, s6, s5
	s_mul_hi_u32 s5, s1, s6
	s_mul_i32 s6, s5, s0
	s_sub_i32 s1, s1, s6
	s_add_i32 s7, s5, 1
	s_sub_i32 s6, s1, s0
	s_cmp_ge_u32 s1, s0
	s_cselect_b32 s5, s7, s5
	s_cselect_b32 s1, s6, s1
	s_add_i32 s6, s5, 1
	s_cmp_ge_u32 s1, s0
	s_cselect_b32 s0, s6, s5
	s_xor_b32 s0, s0, s4
	s_sub_i32 s1, s0, s4
	s_mul_i32 s0, s1, s87
	s_sub_i32 s4, 0x400, s0
	s_min_i32 s1, s4, s1
	s_cmpk_lt_i32 s0, 0x400
	s_cselect_b32 s28, s1, 0
	s_cmp_lt_i32 s28, 1
	s_cbranch_scc1 .LBB0_1497
	s_lshl_b32 s1, s87, 2
	s_andn2_b32 s1, s1, 63
	s_and_b32 s4, s87, 15
	s_or_b32 s1, s1, s4
	s_cmpk_eq_i32 s33, 0x100
	s_cselect_b64 s[6:7], -1, 0
	s_and_b64 s[4:5], s[6:7], exec
	s_cselect_b32 s29, s1, s0
	s_ashr_i32 s8, s29, 6
	s_bfe_u32 s13, s29, 0x30003
	s_ashr_i32 s9, s8, 31
	s_lshl_b32 s0, s13, 6
	s_lshl_b64 s[18:19], s[8:9], 20
	s_lshl_b64 s[4:5], s[8:9], 21
	s_add_u32 s1, s10, s4
	s_addc_u32 s4, s11, s5
	s_lshl_b32 s5, s13, 7
	v_mov_b32_e32 v3, v0
	s_add_u32 s24, s1, s5
	s_addc_u32 s25, s4, 0
	v_readfirstlane_b32 s14, v3
	s_ashr_i32 s22, s14, 6
	s_lshl_b32 s1, s22, 4
	v_bfe_u32 v5, v3, 2, 4
	v_and_or_b32 v2, s1, 48, v5
	s_ashr_i32 s1, s14, 3
	s_andn2_b32 s1, s1, 31
	v_bfe_u32 v6, v3, 4, 2
	v_lshl_add_u32 v8, v2, 9, s1
	s_lshl_b32 s1, s22, 9
	s_lshl_b32 s15, s22, 10
	v_bitop3_b32 v1, v6, v3, 3 bitop3:0x78
	s_cmp_lg_u32 0, -1
	v_lshlrev_b32_e32 v2, 3, v1
	s_cselect_b32 s4, 0, 0
	v_or_b32_e32 v1, v8, v2
	s_add_i32 s38, s15, s4
	v_lshlrev_b32_e32 v1, 1, v1
	v_lshlrev_b32_e32 v9, 5, v5
	s_add_i32 s39, s38, 0x2000
	s_nop 4
	s_mov_b32 s12, m0
	s_mov_b32 m0, s38
	s_nop 0
	global_load_lds_dwordx4 v1, s[24:25]
	s_mov_b32 m0, s12
	v_or3_b32 v9, s1, v9, v2
	s_cmp_lt_i32 s22, 4
	v_readlane_b32 s16, v244, 46
	v_and_b32_e32 v4, 63, v3
	v_and_b32_e32 v7, 3, v3
	v_lshlrev_b32_e32 v180, 1, v9
	s_mov_b32 s1, 0
	s_cselect_b64 s[4:5], -1, 0
	s_cmp_gt_i32 s22, 3
	v_readlane_b32 s17, v244, 47
	s_cbranch_scc1 .LBB0_1471
	s_lshl_b64 s[24:25], s[8:9], 17
	s_add_u32 s24, s16, s24
	s_addc_u32 s25, s17, s25
	s_nop 4
	s_mov_b32 s12, m0
	s_mov_b32 m0, s39
	s_nop 0
	global_load_lds_dwordx4 v180, s[24:25]
	s_mov_b32 m0, s12
.LBB0_1471:
	s_and_b32 s14, s14, 0x3fffffc0
	s_lshl_b32 s14, s14, 2
	s_lshl_b32 s12, s22, 5
	s_add_i32 s42, s14, 0
	s_cmp_lg_u32 0, -1
	s_cselect_b32 s14, 0, 0
	s_add_i32 s14, s14, s15
	s_add_i32 s43, s14, 0x6000
	s_mul_i32 s14, s22, 0x1800
	s_add_i32 s14, s14, 0
	s_add_i32 s24, s14, 0x12800
	s_lshl_b64 s[14:15], s[8:9], 11
	s_lshl_b32 s8, s29, 8
	s_and_b32 s48, s8, 0x700
	s_lshl_b64 s[8:9], s[18:19], 1
	s_add_u32 s8, s34, s8
	s_addc_u32 s9, s35, s9
	s_lshl_b32 s18, s0, 1
	s_add_u32 s8, s8, s18
	s_addc_u32 s9, s9, 0
	s_or_b32 s25, s14, s48
	s_mulk_i32 s13, 0xc0
	s_add_u32 s18, s30, s13
	v_lshlrev_b32_e32 v7, 3, v7
	s_addc_u32 s19, s31, 0
	v_or_b32_e32 v8, v8, v7
	s_and_b64 s[6:7], s[6:7], exec
	v_lshlrev_b32_e32 v181, 1, v8
	s_cselect_b32 s44, 4, 0
	s_ashr_i32 s13, s12, 31
	v_or_b32_e32 v8, s25, v5
	v_mov_b32_e32 v9, s15
	v_lshl_add_u64 v[8:9], v[8:9], 0, s[12:13]
	s_movk_i32 s45, 0x600
	v_mov_b64_e32 v[10:11], s[18:19]
	v_mad_u64_u32 v[10:11], s[6:7], v8, s45, v[10:11]
	v_mad_i32_i24 v11, v9, s45, v11
	v_mov_b32_e32 v167, 0
	v_lshlrev_b32_e32 v166, 1, v2
	s_movk_i32 s23, 0x6000
	v_lshl_add_u64 v[8:9], v[10:11], 0, v[166:167]
	s_nop 4
	s_mov_b32 s6, m0
	s_mov_b32 m0, s43
	s_nop 0
	global_load_lds_dwordx4 v181, s[8:9]
	s_mov_b32 m0, s6
	v_add_co_u32_e32 v10, vcc, s23, v8
	v_lshlrev_b32_e32 v6, 5, v6
	s_nop 0
	v_addc_co_u32_e32 v11, vcc, 0, v9, vcc
	global_load_dwordx4 v[98:101], v[8:9], off
	global_load_dwordx4 v[102:105], v[8:9], off offset:64
	global_load_dwordx4 v[106:109], v[10:11], off
	global_load_dwordx4 v[110:113], v[8:9], off offset:128
	global_load_dwordx4 v[114:117], v[10:11], off offset:64
	global_load_dwordx4 v[118:121], v[10:11], off offset:128
	v_lshrrev_b32_e32 v9, 5, v4
	v_and_b32_e32 v6, 32, v6
	v_lshlrev_b32_e32 v12, 4, v3
	v_add3_u32 v6, 0, v6, v7
	v_lshlrev_b32_e32 v7, 8, v9
	v_and_b32_e32 v12, 0xc0, v12
	v_add3_u32 v183, v6, v7, v12
	v_lshrrev_b32_e32 v6, 2, v3
	v_and_b32_e32 v8, 31, v3
	v_bitop3_b32 v6, v9, v6, 3 bitop3:0x78
	s_lshl_b32 s8, s22, 12
	v_lshlrev_b32_e32 v10, 6, v3
	v_lshlrev_b32_e32 v184, 4, v6
	v_or_b32_e32 v168, s12, v5
	s_add_i32 s8, s8, 0
	v_lshlrev_b32_e32 v5, 9, v9
	v_lshlrev_b32_e32 v6, 1, v8
	v_and_b32_e32 v11, 0x400, v10
	v_and_b32_e32 v10, 0x3c0, v10
	v_add3_u32 v188, s8, v5, v6
	v_lshrrev_b32_e32 v5, 3, v4
	v_lshlrev_b32_e32 v3, 3, v3
	v_add3_u32 v182, 0, v11, v10
	v_lshlrev_b32_e32 v7, 4, v4
	v_add3_u32 v185, s24, v11, v10
	v_cmp_gt_u32_e64 s[6:7], 32, v4
	v_lshl_add_u32 v186, v8, 2, s42
	v_lshlrev_b32_e32 v187, 4, v9
	v_and_b32_e32 v4, 56, v3
	v_lshlrev_b32_e32 v9, 7, v5
	v_lshlrev_b32_e32 v6, 10, v5
	v_or_b32_e32 v8, 8, v5
	v_or_b32_e32 v10, 16, v5
	v_or_b32_e32 v5, 24, v5
	v_mov_b32_e32 v169, s13
	v_lshl_add_u32 v3, v4, 1, s8
	v_lshlrev_b32_e32 v11, 7, v8
	v_lshlrev_b32_e32 v8, 10, v8
	v_lshlrev_b32_e32 v13, 7, v10
	v_lshlrev_b32_e32 v10, 10, v10
	v_lshlrev_b32_e32 v14, 7, v5
	v_lshlrev_b32_e32 v12, 10, v5
	s_add_u32 s13, s16, 0x2000
	v_lshlrev_b32_e32 v170, 1, v2
	v_bfrev_b32_e32 v2, 1
	v_xor_b32_e32 v189, 32, v184
	s_addc_u32 s46, s17, 0
	v_add_u32_e32 v190, s24, v7
	s_mov_b32 s47, 0x41000000
	v_lshlrev_b32_e32 v166, 1, v4
	v_add_u32_e32 v191, v3, v9
	v_lshlrev_b32_e32 v172, 1, v6
	v_add_u32_e32 v192, v3, v11
	v_lshlrev_b32_e32 v174, 1, v8
	v_add_u32_e32 v193, v3, v13
	v_lshlrev_b32_e32 v176, 1, v10
	s_waitcnt lgkmcnt(0)
	v_add_u32_e32 v194, v3, v14
	v_lshlrev_b32_e32 v178, 1, v12
	v_mov_b32_e32 v3, v2
	v_mov_b32_e32 v4, v2
	v_mov_b32_e32 v5, v2
	v_mov_b32_e32 v6, v2
	v_mov_b32_e32 v7, v2
	v_mov_b32_e32 v8, v2
	v_mov_b32_e32 v9, v2
	v_mov_b32_e32 v10, v2
	v_mov_b32_e32 v11, v2
	v_mov_b32_e32 v12, v2
	v_mov_b32_e32 v13, v2
	v_mov_b32_e32 v14, v2
	v_mov_b32_e32 v15, v2
	v_mov_b32_e32 v16, v2
	v_mov_b32_e32 v17, v2
	s_mov_b32 s49, s1
	s_mov_b32 s50, s1
	s_branch .LBB0_1473

.LBB0_1473:
	v_mov_b64_e32 v[32:33], v[16:17]
	v_mov_b64_e32 v[30:31], v[14:15]
	v_mov_b64_e32 v[28:29], v[12:13]
	v_mov_b64_e32 v[26:27], v[10:11]
	v_mov_b64_e32 v[24:25], v[8:9]
	v_mov_b64_e32 v[22:23], v[6:7]
	v_mov_b64_e32 v[20:21], v[4:5]
	v_mov_b64_e32 v[18:19], v[2:3]
	s_waitcnt vmcnt(0) lgkmcnt(0)
	s_barrier
	s_waitcnt vmcnt(0)
	ds_write_b128 v190, v[98:101]
	ds_write_b128 v190, v[106:109] offset:1024
	ds_write_b128 v190, v[102:105] offset:2048
	ds_write_b128 v190, v[114:117] offset:3072
	ds_write_b128 v190, v[110:113] offset:4096
	ds_write_b128 v190, v[118:121] offset:5120
	v_add_u32_e32 v34, v185, v184
	s_mul_i32 s8, s49, 0x3000
	v_add_u32_e32 v35, v185, v189
	ds_read_b128 v[98:101], v34
	ds_read_b128 v[102:105], v34 offset:2048
	ds_read_b128 v[106:109], v35
	ds_read_b128 v[110:113], v34 offset:4096
	ds_read_b128 v[114:117], v35 offset:2048
	ds_read_b128 v[118:121], v35 offset:4096
	v_add_u32_e32 v34, s8, v182
	v_add_u32_e32 v35, v34, v184
	v_add_u32_e32 v34, v34, v189
	ds_read_b128 v[94:97], v35
	ds_read_b128 v[86:89], v35 offset:2048
	ds_read_b128 v[90:93], v34
	ds_read_b128 v[82:85], v34 offset:2048
	ds_read_b128 v[78:81], v35 offset:4096
	ds_read_b128 v[74:77], v35 offset:6144
	ds_read_b128 v[70:73], v34 offset:4096
	ds_read_b128 v[66:69], v34 offset:6144
	ds_read_b128 v[62:65], v35 offset:8192
	ds_read_b128 v[58:61], v35 offset:10240
	ds_read_b128 v[54:57], v34 offset:8192
	ds_read_b128 v[50:53], v34 offset:10240
	s_lshl_b64 s[18:19], s[0:1], 1
	s_add_u32 s26, s10, s18
	s_addc_u32 s27, s11, s19
	s_or_b32 s24, s14, 64
	s_mov_b32 s25, s15
	s_lshl_b64 s[22:23], s[24:25], 9
	s_lshl_b64 s[8:9], s[24:25], 10
	s_add_u32 s52, s26, s8
	s_addc_u32 s53, s27, s9
	s_xor_b32 s51, s49, 1
	s_mul_i32 s0, s51, 0x3000
	s_add_i32 s54, s0, s38
	s_nop 4
	s_mov_b32 s55, m0
	s_mov_b32 m0, s54
	s_nop 0
	global_load_lds_dwordx4 v1, s[52:53]
	s_mov_b32 m0, s55
	v_cndmask_b32_e64 v34, 0, 1, s[4:5]
	v_cmp_ne_u32_e64 s[8:9], 1, v34
	s_andn2_b64 vcc, exec, s[4:5]
	s_cbranch_vccnz .LBB0_1475
	s_lshl_b64 s[24:25], s[24:25], 6
	s_add_u32 s24, s16, s24
	s_addc_u32 s25, s17, s25
	s_add_i32 s0, s0, s39
	s_nop 4
	s_mov_b32 s52, m0
	s_mov_b32 m0, s0
	s_nop 0
	global_load_lds_dwordx4 v180, s[24:25]
	s_mov_b32 m0, s52
.LBB0_1475:
	s_add_u32 s0, s34, s18
	s_addc_u32 s24, s35, s19
	s_lshl_b64 s[22:23], s[22:23], 1
	s_add_u32 s22, s0, s22
	s_addc_u32 s23, s24, s23
	s_lshl_b32 s25, s51, 13
	s_add_i32 s25, s25, s43
	s_nop 4
	s_mov_b32 s52, m0
	s_mov_b32 m0, s25
	s_nop 0
	global_load_lds_dwordx4 v181, s[22:23]
	s_mov_b32 m0, s52
	s_waitcnt lgkmcnt(11)
	v_mfma_f32_32x32x16_bf16 v[34:49], v[94:97], v[98:101], v[18:33]
	s_waitcnt lgkmcnt(10)
	v_mfma_f32_32x32x16_bf16 v[18:33], v[86:89], v[98:101], v[18:33]
	s_waitcnt lgkmcnt(9)
	v_mfma_f32_32x32x16_bf16 v[34:49], v[90:93], v[106:109], v[34:49]
	s_waitcnt lgkmcnt(8)
	v_mfma_f32_32x32x16_bf16 v[18:33], v[82:85], v[106:109], v[18:33]
	s_waitcnt lgkmcnt(7)
	v_mfma_f32_32x32x16_bf16 v[34:49], v[78:81], v[102:105], v[34:49]
	s_waitcnt lgkmcnt(6)
	v_mfma_f32_32x32x16_bf16 v[18:33], v[74:77], v[102:105], v[18:33]
	s_waitcnt lgkmcnt(5)
	v_mfma_f32_32x32x16_bf16 v[34:49], v[70:73], v[114:117], v[34:49]
	s_waitcnt lgkmcnt(4)
	v_mfma_f32_32x32x16_bf16 v[18:33], v[66:69], v[114:117], v[18:33]
	s_waitcnt lgkmcnt(3)
	v_mfma_f32_32x32x16_bf16 v[34:49], v[62:65], v[110:113], v[34:49]
	v_lshl_add_u32 v62, s49, 13, v183
	ds_read_b64_tr_b16 v[94:95], v62 offset:24576
	ds_read_b64_tr_b16 v[96:97], v62 offset:25088
	ds_read_b64_tr_b16 v[90:91], v62 offset:25600
	ds_read_b64_tr_b16 v[92:93], v62 offset:26112
	ds_read_b64_tr_b16 v[86:87], v62 offset:26624
	ds_read_b64_tr_b16 v[88:89], v62 offset:27136
	ds_read_b64_tr_b16 v[82:83], v62 offset:27648
	ds_read_b64_tr_b16 v[84:85], v62 offset:28160
	ds_read_b64_tr_b16 v[78:79], v62 offset:28672
	ds_read_b64_tr_b16 v[80:81], v62 offset:29184
	ds_read_b64_tr_b16 v[74:75], v62 offset:29696
	ds_read_b64_tr_b16 v[76:77], v62 offset:30208
	ds_read_b64_tr_b16 v[70:71], v62 offset:30720
	ds_read_b64_tr_b16 v[72:73], v62 offset:31232
	ds_read_b64_tr_b16 v[66:67], v62 offset:31744
	ds_read_b64_tr_b16 v[68:69], v62 offset:32256
	s_waitcnt lgkmcnt(14)
	v_mfma_f32_32x32x16_bf16 v[18:33], v[58:61], v[110:113], v[18:33]
	v_mfma_f32_32x32x16_bf16 v[34:49], v[54:57], v[118:121], v[34:49]
	v_mfma_f32_32x32x16_bf16 v[18:33], v[50:53], v[118:121], v[18:33]
	s_nop 10
	v_max_f32_e32 v50, v35, v35
	v_max_f32_e32 v51, v34, v34
	v_max_f32_e32 v50, v51, v50
	v_max3_f32 v51, v36, v37, v19
	v_max3_f32 v50, v50, v18, v20
	v_max3_f32 v50, v50, v21, v38
	v_max3_f32 v51, v51, v40, v41
	v_max3_f32 v50, v50, v39, v22
	v_max3_f32 v51, v51, v24, v25
	v_max3_f32 v50, v50, v23, v42
	v_max3_f32 v51, v51, v44, v45
	v_max3_f32 v50, v50, v43, v26
	v_max3_f32 v51, v51, v28, v29
	v_max3_f32 v50, v50, v27, v46
	v_max3_f32 v51, v51, v48, v49
	v_max3_f32 v50, v50, v47, v30
	v_max3_f32 v51, v51, v32, v33
	v_max3_f32 v50, v50, v31, v51
	v_mov_b32_e32 v51, v50
	s_nop 1
	v_permlane32_swap_b32_e32 v50, v51
	v_max_f32_e32 v51, v51, v51
	v_max_f32_e32 v50, v50, v50
	v_max_f32_e32 v122, v50, v51
	v_sub_f32_e32 v18, v18, v122
	v_sub_f32_e32 v19, v19, v122
	v_sub_f32_e32 v34, v34, v122
	v_sub_f32_e32 v35, v35, v122
	v_exp_f32_e32 v34, v34
	v_exp_f32_e32 v127, v18
	v_exp_f32_e32 v18, v35
	v_exp_f32_e32 v128, v19
	v_sub_f32_e32 v20, v20, v122
	v_sub_f32_e32 v36, v36, v122
	v_exp_f32_e32 v19, v36
	v_exp_f32_e32 v129, v20
	v_sub_f32_e32 v21, v21, v122
	v_sub_f32_e32 v22, v22, v122
	v_sub_f32_e32 v23, v23, v122
	v_sub_f32_e32 v24, v24, v122
	v_sub_f32_e32 v25, v25, v122
	v_sub_f32_e32 v37, v37, v122
	v_sub_f32_e32 v38, v38, v122
	v_sub_f32_e32 v39, v39, v122
	v_sub_f32_e32 v40, v40, v122
	v_sub_f32_e32 v41, v41, v122
	v_exp_f32_e32 v20, v37
	v_exp_f32_e32 v130, v21
	v_exp_f32_e32 v21, v38
	v_exp_f32_e32 v38, v22
	v_exp_f32_e32 v22, v39
	v_exp_f32_e32 v39, v23
	v_exp_f32_e32 v23, v40
	v_exp_f32_e32 v40, v24
	v_exp_f32_e32 v131, v25
	v_add_f32_e32 v24, v34, v18
	v_add_f32_e32 v25, v127, v128
	v_exp_f32_e32 v41, v41
	v_cvt_pk_bf16_f32 v34, v34, v18
	v_add_f32_e32 v24, v24, v19
	v_add_f32_e32 v25, v25, v129
	v_cvt_pk_bf16_f32 v35, v19, v20
	v_add_f32_e32 v24, v24, v20
	v_add_f32_e32 v25, v25, v130
	v_cvt_pk_bf16_f32 v36, v21, v22
	v_cvt_pk_bf16_f32 v37, v23, v41
	v_add_f32_e32 v24, v21, v24
	v_add_f32_e32 v25, v38, v25
	v_sub_f32_e32 v42, v42, v122
	v_sub_f32_e32 v43, v43, v122
	v_sub_f32_e32 v44, v44, v122
	v_sub_f32_e32 v45, v45, v122
	v_sub_f32_e32 v46, v46, v122
	v_sub_f32_e32 v47, v47, v122
	v_sub_f32_e32 v48, v48, v122
	v_sub_f32_e32 v49, v49, v122
	v_add_f32_e32 v24, v22, v24
	v_add_f32_e32 v25, v39, v25
	v_sub_f32_e32 v26, v26, v122
	v_sub_f32_e32 v27, v27, v122
	v_sub_f32_e32 v28, v28, v122
	v_sub_f32_e32 v29, v29, v122
	v_sub_f32_e32 v30, v30, v122
	v_sub_f32_e32 v31, v31, v122
	v_sub_f32_e32 v32, v32, v122
	v_sub_f32_e32 v33, v33, v122
	v_exp_f32_e32 v42, v42
	v_exp_f32_e32 v43, v43
	v_exp_f32_e32 v44, v44
	v_exp_f32_e32 v45, v45
	v_exp_f32_e32 v136, v46
	v_exp_f32_e32 v138, v47
	v_exp_f32_e32 v140, v48
	v_exp_f32_e32 v142, v49
	v_exp_f32_e32 v132, v26
	v_exp_f32_e32 v133, v27
	v_exp_f32_e32 v134, v28
	v_exp_f32_e32 v135, v29
	v_exp_f32_e32 v137, v30
	v_exp_f32_e32 v139, v31
	v_exp_f32_e32 v141, v32
	v_exp_f32_e32 v143, v33
	v_add_f32_e32 v46, v23, v24
	v_add_f32_e32 v47, v40, v25
	v_mfma_f32_32x32x16_bf16 v[18:33], v[34:37], v[94:97], 0
	v_add_f32_e32 v171, 0, v122
	v_exp_f32_e64 v126, -v122
	v_cvt_pk_bf16_f32 v122, v42, v43
	v_cvt_pk_bf16_f32 v123, v44, v45
	v_cvt_pk_bf16_f32 v124, v136, v138
	v_cvt_pk_bf16_f32 v125, v140, v142
	v_cvt_pk_bf16_f32 v94, v127, v128
	v_cvt_pk_bf16_f32 v95, v129, v130
	s_waitcnt lgkmcnt(12)
	v_mfma_f32_32x32x16_bf16 v[18:33], v[122:125], v[90:93], v[18:33]
	v_cvt_pk_bf16_f32 v96, v38, v39
	v_cvt_pk_bf16_f32 v97, v40, v131
	v_cvt_pk_bf16_f32 v90, v132, v133
	v_add_f32_e32 v41, v41, v46
	s_waitcnt lgkmcnt(10)
	v_mfma_f32_32x32x16_bf16 v[18:33], v[94:97], v[86:89], v[18:33]
	v_add_f32_e32 v38, v42, v41
	v_add_f32_e32 v46, v131, v47
	v_cvt_pk_bf16_f32 v91, v134, v135
	v_cvt_pk_bf16_f32 v92, v137, v139
	v_cvt_pk_bf16_f32 v93, v141, v143
	v_add_f32_e32 v38, v43, v38
	v_add_f32_e32 v39, v132, v46
	s_waitcnt lgkmcnt(8)
	v_mfma_f32_32x32x16_bf16 v[18:33], v[90:93], v[82:85], v[18:33]
	v_add_f32_e32 v39, v133, v39
	v_add_f32_e32 v38, v44, v38
	s_lshl_b64 s[22:23], s[14:15], 6
	v_add_f32_e32 v82, v134, v39
	v_add_f32_e32 v83, v45, v38
	s_waitcnt lgkmcnt(6)
	v_mfma_f32_32x32x16_bf16 v[34:49], v[34:37], v[78:81], 0
	s_add_u32 s22, s13, s22
	v_add_f32_e32 v78, v135, v82
	v_add_f32_e32 v79, v136, v83
	v_add_f32_e32 v78, v137, v78
	s_waitcnt lgkmcnt(4)
	v_mfma_f32_32x32x16_bf16 v[34:49], v[122:125], v[74:77], v[34:49]
	v_xor_b32_e32 v50, 0x80000000, v171
	v_add_f32_e32 v74, v138, v79
	v_add_f32_e32 v75, v139, v78
	s_waitcnt lgkmcnt(2)
	v_mfma_f32_32x32x16_bf16 v[34:49], v[94:97], v[70:73], v[34:49]
	v_add_f32_e32 v74, v140, v74
	v_add_f32_e32 v75, v141, v75
	s_addc_u32 s23, s46, s23
	s_lshl_b64 s[54:55], s[14:15], 10
	v_mov_b32_e32 v51, v50
	v_mov_b32_e32 v52, v50
	v_mov_b32_e32 v53, v50
	s_waitcnt lgkmcnt(0)
	v_mfma_f32_32x32x16_bf16 v[34:49], v[90:93], v[66:69], v[34:49]
	v_mov_b32_e32 v54, v50
	v_mov_b32_e32 v55, v50
	v_mov_b32_e32 v56, v50
	v_mov_b32_e32 v57, v50
	v_mov_b32_e32 v58, v50
	v_mov_b32_e32 v59, v50
	v_mov_b32_e32 v60, v50
	v_mov_b32_e32 v61, v50
	v_mov_b32_e32 v62, v50
	v_mov_b32_e32 v63, v50
	v_mov_b32_e32 v64, v50
	v_mov_b32_e32 v65, v50
	s_add_u32 s0, s0, s54
	v_add_f32_e32 v70, v142, v74
	v_add_f32_e32 v71, v143, v75
	s_waitcnt vmcnt(0) lgkmcnt(0)
	s_barrier
	s_addc_u32 s53, s24, s55
	v_add_f32_e32 v173, v70, v71
	s_add_u32 s54, s26, s54
	v_fmac_f32_e32 v173, 0, v126
	s_addc_u32 s55, s27, s55
	s_mov_b64 s[24:25], 0x20000
	s_mov_b32 s49, s51
.LBB0_1476:
	s_mul_i32 s52, s49, 0x3000
	v_add_u32_e32 v66, s52, v182
	v_add_u32_e32 v67, v66, v184
	v_add_u32_e32 v66, v66, v189
	ds_read_b128 v[82:85], v67
	ds_read_b128 v[158:161], v67 offset:2048
	ds_read_b128 v[162:165], v66
	ds_read_b128 v[150:153], v66 offset:2048
	ds_read_b128 v[146:149], v67 offset:4096
	ds_read_b128 v[142:145], v67 offset:6144
	ds_read_b128 v[138:141], v66 offset:4096
	ds_read_b128 v[134:137], v66 offset:6144
	ds_read_b128 v[130:133], v67 offset:8192
	ds_read_b128 v[126:129], v67 offset:10240
	ds_read_b128 v[122:125], v66 offset:8192
	ds_read_b128 v[154:157], v66 offset:10240
	s_add_u32 s26, s54, s24
	s_addc_u32 s27, s55, s25
	s_xor_b32 s57, s49, 1
	s_mul_i32 s56, s57, 0x3000
	s_add_i32 s51, s56, s38
	s_nop 4
	s_mov_b32 s58, m0
	s_mov_b32 m0, s51
	s_nop 0
	global_load_lds_dwordx4 v1, s[26:27]
	s_mov_b32 m0, s58
	s_and_b64 vcc, exec, s[8:9]
	s_cbranch_vccnz .LBB0_1478
	s_add_i32 s26, s56, s39
	s_nop 4
	s_mov_b32 s27, m0
	s_mov_b32 m0, s26
	s_nop 0
	global_load_lds_dwordx4 v180, s[22:23]
	s_mov_b32 m0, s27
.LBB0_1478:
	s_add_u32 s26, s0, s24
	s_addc_u32 s27, s53, s25
	s_lshl_b32 s51, s57, 13
	s_add_i32 s58, s51, s43
	s_nop 4
	s_mov_b32 s59, m0
	s_mov_b32 m0, s58
	s_nop 0
	global_load_lds_dwordx4 v181, s[26:27]
	s_mov_b32 m0, s59
	s_waitcnt lgkmcnt(11)
	v_mfma_f32_32x32x16_bf16 v[66:81], v[82:85], v[98:101], v[50:65]
	s_lshl_b32 s58, s49, 13
	s_waitcnt lgkmcnt(10)
	v_mfma_f32_32x32x16_bf16 v[82:97], v[158:161], v[98:101], v[50:65]
	v_add_u32_e32 v158, s58, v183
	s_waitcnt lgkmcnt(9)
	v_mfma_f32_32x32x16_bf16 v[66:81], v[162:165], v[106:109], v[66:81]
	s_waitcnt lgkmcnt(8)
	v_mfma_f32_32x32x16_bf16 v[82:97], v[150:153], v[106:109], v[82:97]
	s_waitcnt lgkmcnt(7)
	v_mfma_f32_32x32x16_bf16 v[66:81], v[146:149], v[102:105], v[66:81]
	s_waitcnt lgkmcnt(6)
	v_mfma_f32_32x32x16_bf16 v[82:97], v[142:145], v[102:105], v[82:97]
	s_waitcnt lgkmcnt(5)
	v_mfma_f32_32x32x16_bf16 v[66:81], v[138:141], v[114:117], v[66:81]
	ds_read_b64_tr_b16 v[150:151], v158 offset:24576
	ds_read_b64_tr_b16 v[152:153], v158 offset:25088
	ds_read_b64_tr_b16 v[146:147], v158 offset:25600
	ds_read_b64_tr_b16 v[148:149], v158 offset:26112
	ds_read_b64_tr_b16 v[142:143], v158 offset:26624
	ds_read_b64_tr_b16 v[144:145], v158 offset:27136
	ds_read_b64_tr_b16 v[138:139], v158 offset:27648
	ds_read_b64_tr_b16 v[140:141], v158 offset:28160
	s_waitcnt lgkmcnt(12)
	v_mfma_f32_32x32x16_bf16 v[82:97], v[134:137], v[114:117], v[82:97]
	s_waitcnt lgkmcnt(11)
	v_mfma_f32_32x32x16_bf16 v[66:81], v[130:133], v[110:113], v[66:81]
	s_waitcnt lgkmcnt(10)
	v_mfma_f32_32x32x16_bf16 v[82:97], v[126:129], v[110:113], v[82:97]
	s_waitcnt lgkmcnt(9)
	v_mfma_f32_32x32x16_bf16 v[66:81], v[122:125], v[118:121], v[66:81]
	ds_read_b64_tr_b16 v[134:135], v158 offset:28672
	ds_read_b64_tr_b16 v[136:137], v158 offset:29184
	ds_read_b64_tr_b16 v[130:131], v158 offset:29696
	ds_read_b64_tr_b16 v[132:133], v158 offset:30208
	ds_read_b64_tr_b16 v[126:127], v158 offset:30720
	ds_read_b64_tr_b16 v[128:129], v158 offset:31232
	ds_read_b64_tr_b16 v[122:123], v158 offset:31744
	ds_read_b64_tr_b16 v[124:125], v158 offset:32256
	s_waitcnt lgkmcnt(14)
	v_mfma_f32_32x32x16_bf16 v[82:97], v[154:157], v[118:121], v[82:97]
	s_nop 1
	v_max_f32_e32 v154, v67, v67
	v_max_f32_e32 v155, v66, v66
	v_max_f32_e32 v154, v155, v154
	s_nop 6
	v_max3_f32 v155, v68, v69, v83
	v_max3_f32 v154, v154, v82, v84
	v_max3_f32 v154, v154, v85, v70
	v_max3_f32 v155, v155, v72, v73
	v_max3_f32 v154, v154, v71, v86
	v_max3_f32 v155, v155, v88, v89
	v_max3_f32 v154, v154, v87, v74
	v_max3_f32 v155, v155, v76, v77
	v_max3_f32 v154, v154, v75, v90
	v_max3_f32 v155, v155, v92, v93
	v_max3_f32 v154, v154, v91, v78
	v_max3_f32 v155, v155, v80, v81
	v_max3_f32 v154, v154, v79, v94
	v_max3_f32 v155, v155, v96, v97
	v_max3_f32 v154, v154, v95, v155
	v_mov_b32_e32 v155, v154
	s_nop 1
	v_permlane32_swap_b32_e32 v154, v155
	v_max_f32_e32 v155, v155, v155
	v_max_f32_e32 v154, v154, v154
	v_max_f32_e32 v154, v154, v155
	v_cmp_lt_f32_e32 vcc, s47, v154
	s_cbranch_vccz .LBB0_1482
	v_max_f32_e32 v50, v154, v154
	v_max_f32_e32 v154, 0, v50
	v_exp_f32_e64 v155, -v154
	v_add_f32_e32 v171, v171, v154
	v_xor_b32_e32 v50, 0x80000000, v171
	v_mov_b32_e32 v51, v50
	v_mov_b32_e32 v52, v50
	v_mov_b32_e32 v53, v50
	v_mov_b32_e32 v54, v50
	v_mov_b32_e32 v55, v50
	v_mov_b32_e32 v56, v50
	v_mov_b32_e32 v57, v50
	v_mov_b32_e32 v58, v50
	v_mov_b32_e32 v59, v50
	v_mov_b32_e32 v60, v50
	v_mov_b32_e32 v61, v50
	v_mov_b32_e32 v62, v50
	v_mov_b32_e32 v63, v50
	v_mov_b32_e32 v64, v50
	v_mov_b32_e32 v65, v50
	s_and_saveexec_b64 s[26:27], s[6:7]
	ds_write_b32 v186, v155 offset:40960
	s_or_b64 exec, exec, s[26:27]
	v_add_u32_e32 v164, s42, v187
	ds_read_b128 v[156:159], v164 offset:41024
	ds_read_b128 v[160:163], v164 offset:41056
	ds_read_b128 v[196:199], v164 offset:40960
	ds_read_b128 v[200:203], v164 offset:40992
	v_pk_add_f32 v[66:67], v[66:67], v[154:155] op_sel_hi:[1,0] neg_lo:[0,1] neg_hi:[0,1]
	v_pk_add_f32 v[82:83], v[82:83], v[154:155] op_sel_hi:[1,0] neg_lo:[0,1] neg_hi:[0,1]
	v_pk_add_f32 v[68:69], v[68:69], v[154:155] op_sel_hi:[1,0] neg_lo:[0,1] neg_hi:[0,1]
	v_pk_add_f32 v[84:85], v[84:85], v[154:155] op_sel_hi:[1,0] neg_lo:[0,1] neg_hi:[0,1]
	v_pk_add_f32 v[70:71], v[70:71], v[154:155] op_sel_hi:[1,0] neg_lo:[0,1] neg_hi:[0,1]
	v_pk_add_f32 v[86:87], v[86:87], v[154:155] op_sel_hi:[1,0] neg_lo:[0,1] neg_hi:[0,1]
	v_pk_add_f32 v[72:73], v[72:73], v[154:155] op_sel_hi:[1,0] neg_lo:[0,1] neg_hi:[0,1]
	v_pk_add_f32 v[88:89], v[88:89], v[154:155] op_sel_hi:[1,0] neg_lo:[0,1] neg_hi:[0,1]
	v_pk_add_f32 v[74:75], v[74:75], v[154:155] op_sel_hi:[1,0] neg_lo:[0,1] neg_hi:[0,1]
	v_pk_add_f32 v[90:91], v[90:91], v[154:155] op_sel_hi:[1,0] neg_lo:[0,1] neg_hi:[0,1]
	v_pk_add_f32 v[76:77], v[76:77], v[154:155] op_sel_hi:[1,0] neg_lo:[0,1] neg_hi:[0,1]
	v_pk_add_f32 v[92:93], v[92:93], v[154:155] op_sel_hi:[1,0] neg_lo:[0,1] neg_hi:[0,1]
	v_pk_add_f32 v[78:79], v[78:79], v[154:155] op_sel_hi:[1,0] neg_lo:[0,1] neg_hi:[0,1]
	v_pk_add_f32 v[94:95], v[94:95], v[154:155] op_sel_hi:[1,0] neg_lo:[0,1] neg_hi:[0,1]
	v_pk_add_f32 v[80:81], v[80:81], v[154:155] op_sel_hi:[1,0] neg_lo:[0,1] neg_hi:[0,1]
	v_pk_add_f32 v[96:97], v[96:97], v[154:155] op_sel_hi:[1,0] neg_lo:[0,1] neg_hi:[0,1]
	v_mul_f32_e32 v173, v173, v155
	s_waitcnt lgkmcnt(2)
	v_pk_mul_f32 v[30:31], v[30:31], v[160:161]
	v_pk_mul_f32 v[26:27], v[26:27], v[156:157]
	s_waitcnt lgkmcnt(0)
	v_pk_mul_f32 v[22:23], v[22:23], v[200:201]
	v_pk_mul_f32 v[32:33], v[32:33], v[162:163]
	v_pk_mul_f32 v[28:29], v[28:29], v[158:159]
	v_pk_mul_f32 v[24:25], v[24:25], v[202:203]
	v_pk_mul_f32 v[20:21], v[20:21], v[198:199]
	v_pk_mul_f32 v[18:19], v[18:19], v[196:197]
	v_pk_mul_f32 v[46:47], v[46:47], v[160:161]
	v_pk_mul_f32 v[42:43], v[42:43], v[156:157]
	v_pk_mul_f32 v[38:39], v[38:39], v[200:201]
	v_pk_mul_f32 v[48:49], v[48:49], v[162:163]
	v_pk_mul_f32 v[44:45], v[44:45], v[158:159]
	v_pk_mul_f32 v[40:41], v[40:41], v[202:203]
	v_pk_mul_f32 v[36:37], v[36:37], v[198:199]
	v_pk_mul_f32 v[34:35], v[34:35], v[196:197]

.LBB0_1484:
	v_add_u32_e32 v66, s56, v182
	v_add_u32_e32 v67, v66, v184
	v_add_u32_e32 v66, v66, v189
	ds_read_b128 v[150:153], v67
	ds_read_b128 v[142:145], v67 offset:2048
	ds_read_b128 v[146:149], v66
	ds_read_b128 v[138:141], v66 offset:2048
	ds_read_b128 v[134:137], v67 offset:4096
	ds_read_b128 v[130:133], v67 offset:6144
	ds_read_b128 v[126:129], v66 offset:4096
	ds_read_b128 v[122:125], v66 offset:6144
	ds_read_b128 v[94:97], v67 offset:8192
	ds_read_b128 v[90:93], v67 offset:10240
	ds_read_b128 v[86:89], v66 offset:8192
	ds_read_b128 v[82:85], v66 offset:10240
	s_add_i32 s26, s50, 1
	s_cmp_lt_u32 s26, s28
	s_cselect_b64 s[22:23], -1, 0
	s_and_b64 s[24:25], s[22:23], exec
	s_cselect_b32 s0, s26, s50
	s_lshl_b32 s50, s0, s44
	s_add_i32 s50, s50, s29
	s_bfe_u32 s27, s50, 0x30003
	s_ashr_i32 s24, s50, 6
	s_ashr_i32 s25, s24, 31
	s_lshl_b32 s0, s27, 6
	s_cmp_ge_u32 s26, s28
	s_cbranch_scc1 .LBB0_1488
	s_lshl_b64 s[54:55], s[24:25], 21
	s_add_u32 s54, s10, s54
	s_addc_u32 s55, s11, s55
	s_lshl_b32 s53, s0, 1
	s_add_u32 s54, s54, s53
	s_addc_u32 s55, s55, 0
	s_add_i32 s56, s52, s38
	s_and_b64 vcc, exec, s[8:9]
	s_nop 4
	s_mov_b32 s8, m0
	s_mov_b32 m0, s56
	s_nop 0
	global_load_lds_dwordx4 v1, s[54:55]
	s_mov_b32 m0, s8
	s_cbranch_vccnz .LBB0_1487
	s_lshl_b64 s[8:9], s[24:25], 17
	s_add_u32 s8, s16, s8
	s_addc_u32 s9, s17, s9
	s_add_i32 s52, s52, s39
	s_nop 4
	s_mov_b32 s54, m0
	s_mov_b32 m0, s52
	s_nop 0
	global_load_lds_dwordx4 v180, s[8:9]
	s_mov_b32 m0, s54
.LBB0_1487:
	s_lshl_b64 s[8:9], s[24:25], 20
	s_lshl_b64 s[8:9], s[8:9], 1
	s_add_u32 s8, s34, s8
	s_addc_u32 s9, s35, s9
	s_add_u32 s8, s8, s53
	s_addc_u32 s9, s9, 0
	s_add_i32 s52, s58, s43
	s_nop 4
	s_mov_b32 s53, m0
	s_mov_b32 m0, s52
	s_nop 0
	global_load_lds_dwordx4 v181, s[8:9]
	s_mov_b32 m0, s53
.LBB0_1488:
	s_waitcnt lgkmcnt(11)
	v_mfma_f32_32x32x16_bf16 v[66:81], v[150:153], v[98:101], v[50:65]
	s_waitcnt lgkmcnt(10)
	v_mfma_f32_32x32x16_bf16 v[50:65], v[142:145], v[98:101], v[50:65]
	s_waitcnt lgkmcnt(9)
	v_mfma_f32_32x32x16_bf16 v[66:81], v[146:149], v[106:109], v[66:81]
	s_waitcnt lgkmcnt(8)
	v_mfma_f32_32x32x16_bf16 v[50:65], v[138:141], v[106:109], v[50:65]
	s_waitcnt lgkmcnt(7)
	v_mfma_f32_32x32x16_bf16 v[66:81], v[134:137], v[102:105], v[66:81]
	s_waitcnt lgkmcnt(6)
	v_mfma_f32_32x32x16_bf16 v[50:65], v[130:133], v[102:105], v[50:65]
	s_waitcnt lgkmcnt(5)
	v_mfma_f32_32x32x16_bf16 v[66:81], v[126:129], v[114:117], v[66:81]
	s_waitcnt lgkmcnt(4)
	v_mfma_f32_32x32x16_bf16 v[50:65], v[122:125], v[114:117], v[50:65]
	s_waitcnt lgkmcnt(3)
	v_mfma_f32_32x32x16_bf16 v[66:81], v[94:97], v[110:113], v[66:81]
	v_add_u32_e32 v94, s51, v183
	ds_read_b64_tr_b16 v[150:151], v94 offset:24576
	ds_read_b64_tr_b16 v[152:153], v94 offset:25088
	ds_read_b64_tr_b16 v[146:147], v94 offset:25600
	ds_read_b64_tr_b16 v[148:149], v94 offset:26112
	ds_read_b64_tr_b16 v[142:143], v94 offset:26624
	ds_read_b64_tr_b16 v[144:145], v94 offset:27136
	ds_read_b64_tr_b16 v[138:139], v94 offset:27648
	ds_read_b64_tr_b16 v[140:141], v94 offset:28160
	ds_read_b64_tr_b16 v[134:135], v94 offset:28672
	ds_read_b64_tr_b16 v[136:137], v94 offset:29184
	ds_read_b64_tr_b16 v[130:131], v94 offset:29696
	ds_read_b64_tr_b16 v[132:133], v94 offset:30208
	ds_read_b64_tr_b16 v[126:127], v94 offset:30720
	ds_read_b64_tr_b16 v[128:129], v94 offset:31232
	ds_read_b64_tr_b16 v[122:123], v94 offset:31744
	ds_read_b64_tr_b16 v[124:125], v94 offset:32256
	s_waitcnt lgkmcnt(14)
	v_mfma_f32_32x32x16_bf16 v[50:65], v[90:93], v[110:113], v[50:65]
	v_mfma_f32_32x32x16_bf16 v[66:81], v[86:89], v[118:121], v[66:81]
	v_mfma_f32_32x32x16_bf16 v[50:65], v[82:85], v[118:121], v[50:65]
	s_nop 10
	v_max_f32_e32 v82, v67, v67
	v_max_f32_e32 v83, v66, v66
	v_max_f32_e32 v82, v83, v82
	v_max3_f32 v83, v68, v69, v51
	v_max3_f32 v82, v82, v50, v52
	v_max3_f32 v82, v82, v53, v70
	v_max3_f32 v83, v83, v72, v73
	v_max3_f32 v82, v82, v71, v54
	v_max3_f32 v83, v83, v56, v57
	v_max3_f32 v82, v82, v55, v74
	v_max3_f32 v83, v83, v76, v77
	v_max3_f32 v82, v82, v75, v58
	v_max3_f32 v83, v83, v60, v61
	v_max3_f32 v82, v82, v59, v78
	v_max3_f32 v83, v83, v80, v81
	v_max3_f32 v82, v82, v79, v62
	v_max3_f32 v83, v83, v64, v65
	v_max3_f32 v82, v82, v63, v83
	v_mov_b32_e32 v83, v82
	s_nop 1
	v_permlane32_swap_b32_e32 v82, v83
	v_max_f32_e32 v83, v83, v83
	v_max_f32_e32 v82, v82, v82
	v_max_f32_e32 v82, v82, v83
	v_cmp_lt_f32_e32 vcc, s47, v82
	s_cbranch_vccz .LBB0_1492
	v_max_f32_e32 v82, v82, v82
	v_max_f32_e32 v154, 0, v82
	v_exp_f32_e64 v155, -v154
	v_add_f32_e32 v82, v171, v154
	v_xor_b32_e32 v82, 0x80000000, v82
	v_mov_b32_e32 v83, v82
	v_mov_b32_e32 v84, v82
	v_mov_b32_e32 v85, v82
	v_mov_b32_e32 v86, v82
	v_mov_b32_e32 v87, v82
	v_mov_b32_e32 v88, v82
	v_mov_b32_e32 v89, v82
	v_mov_b32_e32 v90, v82
	v_mov_b32_e32 v91, v82
	v_mov_b32_e32 v92, v82
	v_mov_b32_e32 v93, v82
	v_mov_b32_e32 v94, v82
	v_mov_b32_e32 v95, v82
	v_mov_b32_e32 v96, v82
	v_mov_b32_e32 v97, v82
	s_and_saveexec_b64 s[8:9], s[6:7]
	ds_write_b32 v186, v155 offset:40960
	s_or_b64 exec, exec, s[8:9]
	v_add_u32_e32 v94, s42, v187
	ds_read_b128 v[82:85], v94 offset:41024
	ds_read_b128 v[86:89], v94 offset:41056
	ds_read_b128 v[90:93], v94 offset:40960
	ds_read_b128 v[94:97], v94 offset:40992
	v_pk_add_f32 v[66:67], v[66:67], v[154:155] op_sel_hi:[1,0] neg_lo:[0,1] neg_hi:[0,1]
	v_pk_add_f32 v[50:51], v[50:51], v[154:155] op_sel_hi:[1,0] neg_lo:[0,1] neg_hi:[0,1]
	v_pk_add_f32 v[68:69], v[68:69], v[154:155] op_sel_hi:[1,0] neg_lo:[0,1] neg_hi:[0,1]
	v_pk_add_f32 v[52:53], v[52:53], v[154:155] op_sel_hi:[1,0] neg_lo:[0,1] neg_hi:[0,1]
	v_pk_add_f32 v[70:71], v[70:71], v[154:155] op_sel_hi:[1,0] neg_lo:[0,1] neg_hi:[0,1]
	v_pk_add_f32 v[54:55], v[54:55], v[154:155] op_sel_hi:[1,0] neg_lo:[0,1] neg_hi:[0,1]
	v_pk_add_f32 v[72:73], v[72:73], v[154:155] op_sel_hi:[1,0] neg_lo:[0,1] neg_hi:[0,1]
	v_pk_add_f32 v[56:57], v[56:57], v[154:155] op_sel_hi:[1,0] neg_lo:[0,1] neg_hi:[0,1]
	v_pk_add_f32 v[74:75], v[74:75], v[154:155] op_sel_hi:[1,0] neg_lo:[0,1] neg_hi:[0,1]
	v_pk_add_f32 v[58:59], v[58:59], v[154:155] op_sel_hi:[1,0] neg_lo:[0,1] neg_hi:[0,1]
	v_pk_add_f32 v[76:77], v[76:77], v[154:155] op_sel_hi:[1,0] neg_lo:[0,1] neg_hi:[0,1]
	v_pk_add_f32 v[60:61], v[60:61], v[154:155] op_sel_hi:[1,0] neg_lo:[0,1] neg_hi:[0,1]
	v_pk_add_f32 v[78:79], v[78:79], v[154:155] op_sel_hi:[1,0] neg_lo:[0,1] neg_hi:[0,1]
	v_pk_add_f32 v[62:63], v[62:63], v[154:155] op_sel_hi:[1,0] neg_lo:[0,1] neg_hi:[0,1]
	v_pk_add_f32 v[80:81], v[80:81], v[154:155] op_sel_hi:[1,0] neg_lo:[0,1] neg_hi:[0,1]
	v_pk_add_f32 v[64:65], v[64:65], v[154:155] op_sel_hi:[1,0] neg_lo:[0,1] neg_hi:[0,1]
	v_mul_f32_e32 v173, v173, v155
	s_waitcnt lgkmcnt(2)
	v_pk_mul_f32 v[30:31], v[30:31], v[86:87]
	v_pk_mul_f32 v[26:27], v[26:27], v[82:83]
	s_waitcnt lgkmcnt(0)
	v_pk_mul_f32 v[22:23], v[22:23], v[94:95]
	v_pk_mul_f32 v[32:33], v[32:33], v[88:89]
	v_pk_mul_f32 v[28:29], v[28:29], v[84:85]
	v_pk_mul_f32 v[24:25], v[24:25], v[96:97]
	v_pk_mul_f32 v[20:21], v[20:21], v[92:93]
	v_pk_mul_f32 v[18:19], v[18:19], v[90:91]
	v_pk_mul_f32 v[46:47], v[46:47], v[86:87]
	v_pk_mul_f32 v[42:43], v[42:43], v[82:83]
	v_pk_mul_f32 v[38:39], v[38:39], v[94:95]
	v_pk_mul_f32 v[48:49], v[48:49], v[88:89]
	v_pk_mul_f32 v[44:45], v[44:45], v[84:85]
	v_pk_mul_f32 v[40:41], v[40:41], v[96:97]
	v_pk_mul_f32 v[36:37], v[36:37], v[92:93]
	v_pk_mul_f32 v[34:35], v[34:35], v[90:91]

.LBB0_1496:
	s_waitcnt vmcnt(0) lgkmcnt(0)
	s_barrier
.LBB0_1497:
	s_cmp_lt_i32 s95, 7
	s_cbranch_scc1 .LBB0_1608
	v_readlane_b32 s4, v244, 42
	v_readlane_b32 s5, v244, 43
	s_mov_b64 s[0:1], -1
	s_and_b64 vcc, exec, s[4:5]
	s_cbranch_vccz .LBB0_1552
	s_waitcnt vmcnt(0)
	s_waitcnt vmcnt(0) lgkmcnt(0)
	s_barrier
	s_mov_b64 s[0:1], exec
	v_readlane_b32 s4, v244, 5
	v_readlane_b32 s5, v244, 6
	v_readlane_b32 s30, v244, 58
	s_and_b64 s[4:5], s[0:1], s[4:5]
	v_readlane_b32 s31, v244, 59
	s_mov_b64 exec, s[4:5]
	s_cbranch_execz .LBB0_1551
	s_add_i32 s4, 0, 0x20160
	v_mov_b32_e32 v1, s4
	s_waitcnt vmcnt(0) expcnt(0) lgkmcnt(0)
	ds_read_b32 v3, v1
	s_add_i32 s4, 0, 0x20164
	v_mov_b32_e32 v1, s4
	ds_read_b32 v1, v1
	s_waitcnt lgkmcnt(1)
	v_cmp_ne_u32_e32 vcc, 0, v3
	s_cbranch_vccnz .LBB0_1515
	v_readlane_b32 s4, v244, 0
	v_readlane_b32 s5, v244, 1
	s_load_dwordx2 s[8:9], s[4:5], 0x4
	s_add_u32 s4, s30, 0x4200
	s_addc_u32 s5, s31, 0
	s_add_u32 s6, s30, 0x4400
	s_addc_u32 s7, s31, 0
	s_waitcnt lgkmcnt(0)
	s_mul_i32 s38, s8, s33
	s_add_u32 s8, s30, 0x4500
	s_mul_i32 s38, s38, s9
	s_addc_u32 s9, s31, 0
	s_add_u32 s10, s30, 0x4600
	s_addc_u32 s11, s31, 0
	s_add_u32 s12, s30, 0x4700
	s_addc_u32 s13, s31, 0
	s_add_u32 s14, s30, 0x4800
	s_addc_u32 s15, s31, 0
	s_add_u32 s16, s30, 0x4900
	s_addc_u32 s17, s31, 0
	s_add_u32 s18, s30, 0x4a00
	s_addc_u32 s19, s31, 0
	s_add_u32 s20, s30, 0x4b00
	s_addc_u32 s21, s31, 0
	s_add_u32 s22, s30, 0x4c00
	s_addc_u32 s23, s31, 0
	s_add_u32 s24, s30, 0x4d00
	s_addc_u32 s25, s31, 0
	s_add_u32 s26, s30, 0x4e00
	s_addc_u32 s27, s31, 0
	s_add_u32 s28, s30, 0x4f00
	s_addc_u32 s29, s31, 0
	s_add_u32 s40, s30, 0x5000
	s_addc_u32 s41, s31, 0
	s_add_u32 s42, s30, 0x5100
	s_addc_u32 s43, s31, 0
	s_add_u32 s44, s30, 0x5200
	s_addc_u32 s45, s31, 0
	s_add_u32 s46, s30, 0x5300
	s_addc_u32 s47, s31, 0
	s_mov_b32 s39, 1
	v_mov_b32_e32 v17, 0
	s_branch .LBB0_1503

.LBB0_1517:
	s_or_b64 exec, exec, s[8:9]
	v_cvt_f32_u32_e32 v5, v3
	s_waitcnt vmcnt(0)
	v_readfirstlane_b32 s6, v4
	v_sub_u32_e32 v4, 0, v3
	v_rcp_iflag_f32_e32 v5, v5
	v_add_u32_e32 v6, s6, v2
	v_mul_f32_e32 v5, 0x4f7ffffe, v5
	v_cvt_u32_f32_e32 v5, v5
	v_mul_lo_u32 v2, v4, v5
	v_mul_hi_u32 v2, v5, v2
	v_add_u32_e32 v2, v5, v2
	v_mul_hi_u32 v2, v6, v2
	v_mul_lo_u32 v4, v2, v3
	v_sub_u32_e32 v4, v6, v4
	v_add_u32_e32 v5, 1, v2
	v_cmp_ge_u32_e32 vcc, v4, v3
	s_nop 1
	v_cndmask_b32_e32 v2, v2, v5, vcc
	v_sub_u32_e32 v5, v4, v3
	v_cndmask_b32_e32 v4, v4, v5, vcc
	v_add_u32_e32 v5, 1, v2
	v_cmp_ge_u32_e32 vcc, v4, v3
	v_add_u32_e32 v4, 1, v6
	s_nop 0
	v_cndmask_b32_e32 v2, v2, v5, vcc
	v_mul_lo_u32 v5, v3, v2
	v_add_u32_e32 v3, v5, v3
	v_cmp_ne_u32_e32 vcc, v4, v3
	s_and_saveexec_b64 s[6:7], vcc
	s_xor_b64 s[6:7], exec, s[6:7]
	s_cbranch_execz .LBB0_1531
	s_waitcnt lgkmcnt(0)
	v_mov_b32_e32 v1, 0x2000
	global_load_dword v1, v1, s[4:5] offset:1024 sc1
	s_add_u32 s12, s4, 0x2400
	s_addc_u32 s13, s5, 0
	s_waitcnt vmcnt(0)
	v_cmp_eq_u32_e32 vcc, v1, v2
	buffer_inv sc1
	s_and_saveexec_b64 s[8:9], vcc
	s_cbranch_execz .LBB0_1530
	s_add_u32 s10, s30, 0x4200
	s_addc_u32 s11, s31, 0
	s_mov_b32 s24, 1
	s_mov_b64 s[14:15], 0
	v_mov_b32_e32 v1, 0
	s_branch .LBB0_1521

.LBB0_1574:
	s_or_b64 exec, exec, s[8:9]
	v_cvt_f32_u32_e32 v4, v2
	s_waitcnt vmcnt(0)
	v_readfirstlane_b32 s6, v3
	v_sub_u32_e32 v3, 0, v2
	v_rcp_iflag_f32_e32 v4, v4
	v_add_u32_e32 v5, s6, v1
	v_mul_f32_e32 v4, 0x4f7ffffe, v4
	v_cvt_u32_f32_e32 v4, v4
	v_mul_lo_u32 v1, v3, v4
	v_mul_hi_u32 v1, v4, v1
	v_add_u32_e32 v1, v4, v1
	v_mul_hi_u32 v1, v5, v1
	v_mul_lo_u32 v3, v1, v2
	v_sub_u32_e32 v3, v5, v3
	v_add_u32_e32 v4, 1, v1
	v_cmp_ge_u32_e32 vcc, v3, v2
	s_nop 1
	v_cndmask_b32_e32 v1, v1, v4, vcc
	v_sub_u32_e32 v4, v3, v2
	v_cndmask_b32_e32 v3, v3, v4, vcc
	v_add_u32_e32 v4, 1, v1
	v_cmp_ge_u32_e32 vcc, v3, v2
	v_add_u32_e32 v3, 1, v5
	s_nop 0
	v_cndmask_b32_e32 v1, v1, v4, vcc
	v_mul_lo_u32 v4, v2, v1
	v_add_u32_e32 v2, v4, v2
	v_cmp_ne_u32_e32 vcc, v3, v2
	s_and_saveexec_b64 s[6:7], vcc
	s_xor_b64 s[6:7], exec, s[6:7]
	s_cbranch_execz .LBB0_1588
	v_mov_b32_e32 v2, 0x2000
	global_load_dword v2, v2, s[4:5] offset:1024 sc1
	s_add_u32 s12, s4, 0x2400
	s_addc_u32 s13, s5, 0
	s_waitcnt vmcnt(0)
	v_cmp_eq_u32_e32 vcc, v2, v1
	s_and_saveexec_b64 s[8:9], vcc
	buffer_inv sc1
	s_cbranch_execz .LBB0_1587
	s_add_u32 s10, s30, 0x4200
	s_addc_u32 s11, s31, 0
	s_mov_b32 s24, 1
	s_mov_b64 s[14:15], 0
	v_mov_b32_e32 v2, 0
	s_branch .LBB0_1578

.LBB0_1670:
	s_or_b64 exec, exec, s[10:11]
	v_cvt_f32_u32_e32 v5, v3
	s_waitcnt vmcnt(0)
	v_readfirstlane_b32 s0, v4
	v_sub_u32_e32 v4, 0, v3
	v_rcp_iflag_f32_e32 v5, v5
	v_add_u32_e32 v6, s0, v2
	v_mul_f32_e32 v5, 0x4f7ffffe, v5
	v_cvt_u32_f32_e32 v5, v5
	v_mul_lo_u32 v2, v4, v5
	v_mul_hi_u32 v2, v5, v2
	v_add_u32_e32 v2, v5, v2
	v_mul_hi_u32 v2, v6, v2
	v_mul_lo_u32 v4, v2, v3
	v_sub_u32_e32 v4, v6, v4
	v_add_u32_e32 v5, 1, v2
	v_cmp_ge_u32_e32 vcc, v4, v3
	s_nop 1
	v_cndmask_b32_e32 v2, v2, v5, vcc
	v_sub_u32_e32 v5, v4, v3
	v_cndmask_b32_e32 v4, v4, v5, vcc
	v_add_u32_e32 v5, 1, v2
	v_cmp_ge_u32_e32 vcc, v4, v3
	v_add_u32_e32 v4, 1, v6
	s_nop 0
	v_cndmask_b32_e32 v2, v2, v5, vcc
	v_mul_lo_u32 v5, v3, v2
	v_add_u32_e32 v3, v5, v3
	v_cmp_ne_u32_e32 vcc, v4, v3
	s_and_saveexec_b64 s[0:1], vcc
	s_xor_b64 s[0:1], exec, s[0:1]
	s_cbranch_execz .LBB0_1684
	s_waitcnt lgkmcnt(0)
	v_mov_b32_e32 v1, 0x2000
	global_load_dword v1, v1, s[8:9] offset:1024 sc1
	s_add_u32 s14, s8, 0x2400
	s_addc_u32 s15, s9, 0
	s_waitcnt vmcnt(0)
	v_cmp_eq_u32_e32 vcc, v1, v2
	s_and_saveexec_b64 s[10:11], vcc
	s_cbranch_execz .LBB0_1683
	buffer_inv sc1
	s_add_u32 s12, s34, 0x4200
	s_addc_u32 s13, s35, 0
	s_mov_b32 s3, 1
	s_mov_b64 s[16:17], 0
	v_mov_b32_e32 v1, 0
	s_branch .LBB0_1674

.LBB0_1750:
	s_or_b64 exec, exec, s[8:9]
	v_cvt_f32_u32_e32 v5, v3
	s_waitcnt vmcnt(0)
	v_readfirstlane_b32 s0, v4
	v_sub_u32_e32 v4, 0, v3
	v_rcp_iflag_f32_e32 v5, v5
	v_add_u32_e32 v6, s0, v2
	v_mul_f32_e32 v5, 0x4f7ffffe, v5
	v_cvt_u32_f32_e32 v5, v5
	v_mul_lo_u32 v2, v4, v5
	v_mul_hi_u32 v2, v5, v2
	v_add_u32_e32 v2, v5, v2
	v_mul_hi_u32 v2, v6, v2
	v_mul_lo_u32 v4, v2, v3
	v_sub_u32_e32 v4, v6, v4
	v_add_u32_e32 v5, 1, v2
	v_cmp_ge_u32_e32 vcc, v4, v3
	s_nop 1
	v_cndmask_b32_e32 v2, v2, v5, vcc
	v_sub_u32_e32 v5, v4, v3
	v_cndmask_b32_e32 v4, v4, v5, vcc
	v_add_u32_e32 v5, 1, v2
	v_cmp_ge_u32_e32 vcc, v4, v3
	v_add_u32_e32 v4, 1, v6
	s_nop 0
	v_cndmask_b32_e32 v2, v2, v5, vcc
	v_mul_lo_u32 v5, v3, v2
	v_add_u32_e32 v3, v5, v3
	v_cmp_ne_u32_e32 vcc, v4, v3
	s_and_saveexec_b64 s[0:1], vcc
	s_xor_b64 s[0:1], exec, s[0:1]
	s_cbranch_execz .LBB0_1764
	s_waitcnt lgkmcnt(0)
	v_mov_b32_e32 v1, 0x2000
	global_load_dword v1, v1, s[6:7] offset:1024 sc1
	s_add_u32 s12, s6, 0x2400
	s_addc_u32 s13, s7, 0
	s_waitcnt vmcnt(0)
	v_cmp_eq_u32_e32 vcc, v1, v2
	s_and_saveexec_b64 s[8:9], vcc
	s_cbranch_execz .LBB0_1763
	buffer_inv sc1
	s_add_u32 s10, s34, 0x4200
	s_addc_u32 s11, s35, 0
	s_mov_b32 s3, 1
	s_mov_b64 s[14:15], 0
	v_mov_b32_e32 v1, 0
	s_branch .LBB0_1754
